# code placement: s_nop pads so the IN/OUT/UP/DOWN K-loop heads sit at byte addresses 0 mod 8 as in the baseline (they had drifted to 4 mod 8); on top of v59
# speedup vs baseline: 1.0013x; 1.0013x over previous
;     __host__ __device__ __forceinline__ bool next(int i, Unit& u) const { const int vv = vid + (i / 5) * G; if (vv >= 256) return false; u.pm = vv >> 2; u.pn = (vv & 3) + 4 * (i % 5); return true; }
;     __host__ __device__ __forceinline__ bool next(int i, pg8::Unit& u) const { const long Lx = (long)i * G + c; if (Lx >= 128) return false; const int Lq = (int)Lx; u.pm = 8 * (Lq >> 5) + (Lq & 7); u.pn = (Lq >> 3) & 3; return true; }
;     __device__ __forceinline__ size_t b_off(const pg8::Unit& u) const { return (size_t)(u.pm >> 3) * 4 * 131072; }
;     ...
;         const bool has_next = S.next(ui + 1, nxt);
;         const char* nA = has_next ? (const char*)g.A + (size_t)nxt.pm * tstepA + (size_t)nxt.pn * APN + kofA : cA; const char* nB = has_next ? (const char*)g.Bt + (size_t)nxt.pn * tstepB + S.b_off(nxt) + kofB : cB;
;     ...
; #pragma unroll
;         for (int a = 0; a < 2; ++a)
; #pragma unroll
;             for (int b = 0; b < 2; ++b)
; #pragma unroll
;                 for (int m = 0; m < 4; ++m)
; #pragma unroll
;                     for (int n = 0; n < 2; ++n) acc[a][b][m][n] = (f32x4){0.f, 0.f, 0.f, 0.f};
;         cur = nxt; cA = nA; cB = nB; ++ui;
.LBB0_327:
	s_ashr_i32 s29, s28, 31
	s_lshl_b64 s[34:35], s[28:29], 20
	s_add_u32 s34, s61, s34
	s_addc_u32 s35, s63, s35
	s_and_b64 s[46:47], s[36:37], exec
	s_cselect_b32 s29, s35, s7
	s_cselect_b32 s54, s34, s6
	s_ashr_i32 s31, s30, 31
	s_lshl_b64 s[46:47], s[30:31], 20
	s_add_u32 s46, s48, s46
	s_addc_u32 s47, s49, s47
	s_and_b64 s[56:57], s[36:37], exec
	s_cselect_b32 s31, s47, s87
	s_cselect_b32 s55, s46, s86
	s_add_u32 s6, s6, 0xc000
	s_addc_u32 s7, s7, 0
	s_add_u32 s56, s86, 0x10000
	v_mov_b32_e32 v2, 0
	s_addc_u32 s57, s87, 0
	s_mov_b32 vcc_lo, -2
	v_mov_b32_e32 v3, v2
	v_mov_b32_e32 v4, v2
	v_mov_b32_e32 v5, v2
	v_mov_b32_e32 v6, v2
	v_mov_b32_e32 v7, v2
	v_mov_b32_e32 v8, v2
	v_mov_b32_e32 v9, v2
	v_mov_b32_e32 v42, v2
	v_mov_b32_e32 v43, v2
	v_mov_b32_e32 v44, v2
	v_mov_b32_e32 v45, v2
	v_mov_b32_e32 v46, v2
	v_mov_b32_e32 v47, v2
	v_mov_b32_e32 v48, v2
	v_mov_b32_e32 v49, v2
	v_mov_b32_e32 v66, v2
	v_mov_b32_e32 v67, v2
	v_mov_b32_e32 v68, v2
	v_mov_b32_e32 v69, v2
	v_mov_b32_e32 v70, v2
	v_mov_b32_e32 v71, v2
	v_mov_b32_e32 v72, v2
	v_mov_b32_e32 v73, v2
	v_mov_b32_e32 v82, v2
	v_mov_b32_e32 v83, v2
	v_mov_b32_e32 v84, v2
	v_mov_b32_e32 v85, v2
	v_mov_b32_e32 v86, v2
	v_mov_b32_e32 v87, v2
	v_mov_b32_e32 v88, v2
	v_mov_b32_e32 v89, v2
	v_mov_b32_e32 v30, v2
	v_mov_b32_e32 v31, v2
	v_mov_b32_e32 v32, v2
	v_mov_b32_e32 v33, v2
	v_mov_b32_e32 v34, v2
	v_mov_b32_e32 v35, v2
	v_mov_b32_e32 v36, v2
	v_mov_b32_e32 v37, v2
	v_mov_b32_e32 v58, v2
	v_mov_b32_e32 v59, v2
	v_mov_b32_e32 v60, v2
	v_mov_b32_e32 v61, v2
	v_mov_b32_e32 v62, v2
	v_mov_b32_e32 v63, v2
	v_mov_b32_e32 v64, v2
	v_mov_b32_e32 v65, v2
	v_mov_b32_e32 v74, v2
	v_mov_b32_e32 v75, v2
	v_mov_b32_e32 v76, v2
	v_mov_b32_e32 v77, v2
	v_mov_b32_e32 v78, v2
	v_mov_b32_e32 v79, v2
	v_mov_b32_e32 v80, v2
	v_mov_b32_e32 v81, v2
	v_mov_b32_e32 v90, v2
	v_mov_b32_e32 v91, v2
	v_mov_b32_e32 v92, v2
	v_mov_b32_e32 v93, v2
	v_mov_b32_e32 v94, v2
	v_mov_b32_e32 v95, v2
	v_mov_b32_e32 v96, v2
	v_mov_b32_e32 v97, v2
	v_mov_b32_e32 v98, v2
	v_mov_b32_e32 v99, v2
	v_mov_b32_e32 v100, v2
	v_mov_b32_e32 v101, v2
	v_mov_b32_e32 v102, v2
	v_mov_b32_e32 v103, v2
	v_mov_b32_e32 v104, v2
	v_mov_b32_e32 v105, v2
	v_mov_b32_e32 v114, v2
	v_mov_b32_e32 v115, v2
	v_mov_b32_e32 v116, v2
	v_mov_b32_e32 v117, v2
	v_mov_b32_e32 v118, v2
	v_mov_b32_e32 v119, v2
	v_mov_b32_e32 v120, v2
	v_mov_b32_e32 v121, v2
	v_mov_b32_e32 v130, v2
	v_mov_b32_e32 v131, v2
	v_mov_b32_e32 v132, v2
	v_mov_b32_e32 v133, v2
	v_mov_b32_e32 v134, v2
	v_mov_b32_e32 v135, v2
	v_mov_b32_e32 v136, v2
	v_mov_b32_e32 v137, v2
	v_mov_b32_e32 v146, v2
	v_mov_b32_e32 v147, v2
	v_mov_b32_e32 v148, v2
	v_mov_b32_e32 v149, v2
	v_mov_b32_e32 v150, v2
	v_mov_b32_e32 v151, v2
	v_mov_b32_e32 v152, v2
	v_mov_b32_e32 v153, v2
	v_mov_b32_e32 v106, v2
	v_mov_b32_e32 v107, v2
	v_mov_b32_e32 v108, v2
	v_mov_b32_e32 v109, v2
	v_mov_b32_e32 v110, v2
	v_mov_b32_e32 v111, v2
	v_mov_b32_e32 v112, v2
	v_mov_b32_e32 v113, v2
	v_mov_b32_e32 v122, v2
	v_mov_b32_e32 v123, v2
	v_mov_b32_e32 v124, v2
	v_mov_b32_e32 v125, v2
	v_mov_b32_e32 v126, v2
	v_mov_b32_e32 v127, v2
	v_mov_b32_e32 v128, v2
	v_mov_b32_e32 v129, v2
	v_mov_b32_e32 v138, v2
	v_mov_b32_e32 v139, v2
	v_mov_b32_e32 v140, v2
	v_mov_b32_e32 v141, v2
	v_mov_b32_e32 v142, v2
	v_mov_b32_e32 v143, v2
	v_mov_b32_e32 v144, v2
	v_mov_b32_e32 v145, v2
	v_mov_b32_e32 v154, v2
	v_mov_b32_e32 v155, v2
	v_mov_b32_e32 v156, v2
	v_mov_b32_e32 v157, v2
	v_mov_b32_e32 v158, v2
	v_mov_b32_e32 v159, v2
	v_mov_b32_e32 v160, v2
	v_mov_b32_e32 v161, v2
	s_nop 0

;     __host__ __device__ __forceinline__ bool next(int i, Unit& u) const { const int vv = vid + (i / 5) * G; if (vv >= 256) return false; u.pm = vv >> 2; u.pn = (vv & 3) + 4 * (i % 5); return true; }
;     __host__ __device__ __forceinline__ bool next(int i, pg8::Unit& u) const { const long Lx = (long)i * G + c; if (Lx >= 128) return false; const int Lq = (int)Lx; u.pm = 8 * (Lq >> 5) + (Lq & 7); u.pn = (Lq >> 3) & 3; return true; }
;     __device__ __forceinline__ size_t b_off(const pg8::Unit& u) const { return (size_t)(u.pm >> 3) * 4 * 131072; }
;     ...
;         const bool has_next = S.next(ui + 1, nxt);
;         const char* nA = has_next ? (const char*)g.A + (size_t)nxt.pm * tstepA + (size_t)nxt.pn * APN + kofA : cA; const char* nB = has_next ? (const char*)g.Bt + (size_t)nxt.pn * tstepB + S.b_off(nxt) + kofB : cB;
;     ...
; #pragma unroll
;         for (int a = 0; a < 2; ++a)
; #pragma unroll
;             for (int b = 0; b < 2; ++b)
; #pragma unroll
;                 for (int m = 0; m < 4; ++m)
; #pragma unroll
;                     for (int n = 0; n < 2; ++n) acc[a][b][m][n] = (f32x4){0.f, 0.f, 0.f, 0.f};
;         cur = nxt; cA = nA; cB = nB; ++ui;
.LBB0_1127:
	s_ashr_i32 s77, s76, 31
	s_lshl_b64 s[24:25], s[76:77], 20
	s_add_u32 s78, s33, s24
	s_addc_u32 s79, s40, s25
	s_and_b64 s[26:27], s[6:7], exec
	s_cselect_b32 s23, s79, s35
	s_cselect_b32 s29, s78, s34
	s_ashr_i32 s73, s72, 31
	s_lshl_b64 s[26:27], s[72:73], 20
	s_add_u32 s96, s41, s26
	s_addc_u32 s97, s48, s27
	s_and_b64 s[46:47], s[6:7], exec
	s_cselect_b32 s21, s97, s37
	s_cselect_b32 s31, s96, s36
	s_add_u32 s34, s34, 0xc000
	s_addc_u32 s35, s35, 0
	s_add_u32 s44, s36, 0x10000
	v_mov_b32_e32 v2, 0
	s_addc_u32 s56, s37, 0
	s_mov_b32 s57, -2
	v_mov_b32_e32 v3, v2
	v_mov_b32_e32 v4, v2
	v_mov_b32_e32 v5, v2
	v_mov_b32_e32 v6, v2
	v_mov_b32_e32 v7, v2
	v_mov_b32_e32 v8, v2
	v_mov_b32_e32 v9, v2
	v_mov_b32_e32 v18, v2
	v_mov_b32_e32 v19, v2
	v_mov_b32_e32 v20, v2
	v_mov_b32_e32 v21, v2
	v_mov_b32_e32 v22, v2
	v_mov_b32_e32 v23, v2
	v_mov_b32_e32 v24, v2
	v_mov_b32_e32 v25, v2
	v_mov_b32_e32 v34, v2
	v_mov_b32_e32 v35, v2
	v_mov_b32_e32 v36, v2
	v_mov_b32_e32 v37, v2
	v_mov_b32_e32 v38, v2
	v_mov_b32_e32 v39, v2
	v_mov_b32_e32 v40, v2
	v_mov_b32_e32 v41, v2
	v_mov_b32_e32 v50, v2
	v_mov_b32_e32 v51, v2
	v_mov_b32_e32 v52, v2
	v_mov_b32_e32 v53, v2
	v_mov_b32_e32 v54, v2
	v_mov_b32_e32 v55, v2
	v_mov_b32_e32 v56, v2
	v_mov_b32_e32 v57, v2
	v_mov_b32_e32 v10, v2
	v_mov_b32_e32 v11, v2
	v_mov_b32_e32 v12, v2
	v_mov_b32_e32 v13, v2
	v_mov_b32_e32 v14, v2
	v_mov_b32_e32 v15, v2
	v_mov_b32_e32 v16, v2
	v_mov_b32_e32 v17, v2
	v_mov_b32_e32 v26, v2
	v_mov_b32_e32 v27, v2
	v_mov_b32_e32 v28, v2
	v_mov_b32_e32 v29, v2
	v_mov_b32_e32 v30, v2
	v_mov_b32_e32 v31, v2
	v_mov_b32_e32 v32, v2
	v_mov_b32_e32 v33, v2
	v_mov_b32_e32 v42, v2
	v_mov_b32_e32 v43, v2
	v_mov_b32_e32 v44, v2
	v_mov_b32_e32 v45, v2
	v_mov_b32_e32 v46, v2
	v_mov_b32_e32 v47, v2
	v_mov_b32_e32 v48, v2
	v_mov_b32_e32 v49, v2
	v_mov_b32_e32 v58, v2
	v_mov_b32_e32 v59, v2
	v_mov_b32_e32 v60, v2
	v_mov_b32_e32 v61, v2
	v_mov_b32_e32 v62, v2
	v_mov_b32_e32 v63, v2
	v_mov_b32_e32 v64, v2
	v_mov_b32_e32 v65, v2
	v_mov_b32_e32 v66, v2
	v_mov_b32_e32 v67, v2
	v_mov_b32_e32 v68, v2
	v_mov_b32_e32 v69, v2
	v_mov_b32_e32 v70, v2
	v_mov_b32_e32 v71, v2
	v_mov_b32_e32 v72, v2
	v_mov_b32_e32 v73, v2
	v_mov_b32_e32 v82, v2
	v_mov_b32_e32 v83, v2
	v_mov_b32_e32 v84, v2
	v_mov_b32_e32 v85, v2
	v_mov_b32_e32 v86, v2
	v_mov_b32_e32 v87, v2
	v_mov_b32_e32 v88, v2
	v_mov_b32_e32 v89, v2
	v_mov_b32_e32 v98, v2
	v_mov_b32_e32 v99, v2
	v_mov_b32_e32 v100, v2
	v_mov_b32_e32 v101, v2
	v_mov_b32_e32 v102, v2
	v_mov_b32_e32 v103, v2
	v_mov_b32_e32 v104, v2
	v_mov_b32_e32 v105, v2
	v_mov_b32_e32 v114, v2
	v_mov_b32_e32 v115, v2
	v_mov_b32_e32 v116, v2
	v_mov_b32_e32 v117, v2
	v_mov_b32_e32 v118, v2
	v_mov_b32_e32 v119, v2
	v_mov_b32_e32 v120, v2
	v_mov_b32_e32 v121, v2
	v_mov_b32_e32 v74, v2
	v_mov_b32_e32 v75, v2
	v_mov_b32_e32 v76, v2
	v_mov_b32_e32 v77, v2
	v_mov_b32_e32 v78, v2
	v_mov_b32_e32 v79, v2
	v_mov_b32_e32 v80, v2
	v_mov_b32_e32 v81, v2
	v_mov_b32_e32 v90, v2
	v_mov_b32_e32 v91, v2
	v_mov_b32_e32 v92, v2
	v_mov_b32_e32 v93, v2
	v_mov_b32_e32 v94, v2
	v_mov_b32_e32 v95, v2
	v_mov_b32_e32 v96, v2
	v_mov_b32_e32 v97, v2
	v_mov_b32_e32 v106, v2
	v_mov_b32_e32 v107, v2
	v_mov_b32_e32 v108, v2
	v_mov_b32_e32 v109, v2
	v_mov_b32_e32 v110, v2
	v_mov_b32_e32 v111, v2
	v_mov_b32_e32 v112, v2
	v_mov_b32_e32 v113, v2
	v_mov_b32_e32 v122, v2
	v_mov_b32_e32 v123, v2
	v_mov_b32_e32 v124, v2
	v_mov_b32_e32 v125, v2
	v_mov_b32_e32 v126, v2
	v_mov_b32_e32 v127, v2
	v_mov_b32_e32 v128, v2
	v_mov_b32_e32 v129, v2
	s_nop 0

;     __host__ __device__ __forceinline__ bool next(int i, Unit& u) const { const int vv = vid + (i / 5) * G; if (vv >= 256) return false; u.pm = vv >> 2; u.pn = (vv & 3) + 4 * (i % 5); return true; }
;     __host__ __device__ __forceinline__ bool next(int i, pg8::Unit& u) const { const long Lx = (long)i * G + c; if (Lx >= 128) return false; const int Lq = (int)Lx; u.pm = 8 * (Lq >> 5) + (Lq & 7); u.pn = (Lq >> 3) & 3; return true; }
;     __device__ __forceinline__ size_t b_off(const pg8::Unit& u) const { return (size_t)(u.pm >> 3) * 4 * 131072; }
;     ...
;         const bool has_next = S.next(ui + 1, nxt);
;         const char* nA = has_next ? (const char*)g.A + (size_t)nxt.pm * tstepA + (size_t)nxt.pn * APN + kofA : cA; const char* nB = has_next ? (const char*)g.Bt + (size_t)nxt.pn * tstepB + S.b_off(nxt) + kofB : cB;
;     ...
; #pragma unroll
;         for (int a = 0; a < 2; ++a)
; #pragma unroll
;             for (int b = 0; b < 2; ++b)
; #pragma unroll
;                 for (int m = 0; m < 4; ++m)
; #pragma unroll
;                     for (int n = 0; n < 2; ++n) acc[a][b][m][n] = (f32x4){0.f, 0.f, 0.f, 0.f};
;         cur = nxt; cA = nA; cB = nB; ++ui;
.LBB0_1255:
	s_ashr_i32 s27, s26, 31
	s_lshl_b64 s[28:29], s[26:27], 20
	s_add_u32 s28, s2, s28
	s_addc_u32 s29, s33, s29
	s_and_b64 s[30:31], s[6:7], exec
	s_cselect_b32 s27, s29, s35
	s_cselect_b32 s57, s28, s34
	s_ashr_i32 s25, s24, 31
	s_lshl_b64 s[30:31], s[24:25], 20
	s_add_u32 s30, s40, s30
	s_addc_u32 s31, s41, s31
	s_and_b64 s[46:47], s[6:7], exec
	s_cselect_b32 s25, s31, s37
	s_cselect_b32 vcc_lo, s30, s36
	s_add_u32 vcc_hi, s36, 0x10000
	v_mov_b32_e32 v10, 0
	s_addc_u32 s65, s37, 0
	s_mov_b32 s66, -2
	v_mov_b32_e32 v11, v10
	v_mov_b32_e32 v12, v10
	v_mov_b32_e32 v13, v10
	v_mov_b32_e32 v14, v10
	v_mov_b32_e32 v15, v10
	v_mov_b32_e32 v16, v10
	v_mov_b32_e32 v17, v10
	v_mov_b32_e32 v18, v10
	v_mov_b32_e32 v19, v10
	v_mov_b32_e32 v20, v10
	v_mov_b32_e32 v21, v10
	v_mov_b32_e32 v22, v10
	v_mov_b32_e32 v23, v10
	v_mov_b32_e32 v24, v10
	v_mov_b32_e32 v25, v10
	v_mov_b32_e32 v50, v10
	v_mov_b32_e32 v51, v10
	v_mov_b32_e32 v52, v10
	v_mov_b32_e32 v53, v10
	v_mov_b32_e32 v54, v10
	v_mov_b32_e32 v55, v10
	v_mov_b32_e32 v56, v10
	v_mov_b32_e32 v57, v10
	v_mov_b32_e32 v58, v10
	v_mov_b32_e32 v59, v10
	v_mov_b32_e32 v60, v10
	v_mov_b32_e32 v61, v10
	v_mov_b32_e32 v62, v10
	v_mov_b32_e32 v63, v10
	v_mov_b32_e32 v64, v10
	v_mov_b32_e32 v65, v10
	v_mov_b32_e32 v2, v10
	v_mov_b32_e32 v3, v10
	v_mov_b32_e32 v4, v10
	v_mov_b32_e32 v5, v10
	v_mov_b32_e32 v38, v10
	v_mov_b32_e32 v39, v10
	v_mov_b32_e32 v40, v10
	v_mov_b32_e32 v41, v10
	v_mov_b32_e32 v6, v10
	v_mov_b32_e32 v7, v10
	v_mov_b32_e32 v8, v10
	v_mov_b32_e32 v9, v10
	v_mov_b32_e32 v42, v10
	v_mov_b32_e32 v43, v10
	v_mov_b32_e32 v44, v10
	v_mov_b32_e32 v45, v10
	v_mov_b32_e32 v66, v10
	v_mov_b32_e32 v67, v10
	v_mov_b32_e32 v68, v10
	v_mov_b32_e32 v69, v10
	v_mov_b32_e32 v70, v10
	v_mov_b32_e32 v71, v10
	v_mov_b32_e32 v72, v10
	v_mov_b32_e32 v73, v10
	v_mov_b32_e32 v74, v10
	v_mov_b32_e32 v75, v10
	v_mov_b32_e32 v76, v10
	v_mov_b32_e32 v77, v10
	v_mov_b32_e32 v78, v10
	v_mov_b32_e32 v79, v10
	v_mov_b32_e32 v80, v10
	v_mov_b32_e32 v81, v10
	v_mov_b32_e32 v82, v10
	v_mov_b32_e32 v83, v10
	v_mov_b32_e32 v84, v10
	v_mov_b32_e32 v85, v10
	v_mov_b32_e32 v86, v10
	v_mov_b32_e32 v87, v10
	v_mov_b32_e32 v88, v10
	v_mov_b32_e32 v89, v10
	v_mov_b32_e32 v90, v10
	v_mov_b32_e32 v91, v10
	v_mov_b32_e32 v92, v10
	v_mov_b32_e32 v93, v10
	v_mov_b32_e32 v94, v10
	v_mov_b32_e32 v95, v10
	v_mov_b32_e32 v96, v10
	v_mov_b32_e32 v97, v10
	v_mov_b32_e32 v34, v10
	v_mov_b32_e32 v35, v10
	v_mov_b32_e32 v36, v10
	v_mov_b32_e32 v37, v10
	v_mov_b32_e32 v26, v10
	v_mov_b32_e32 v27, v10
	v_mov_b32_e32 v28, v10
	v_mov_b32_e32 v29, v10
	v_mov_b32_e32 v46, v10
	v_mov_b32_e32 v47, v10
	v_mov_b32_e32 v48, v10
	v_mov_b32_e32 v49, v10
	v_mov_b32_e32 v30, v10
	v_mov_b32_e32 v31, v10
	v_mov_b32_e32 v32, v10
	v_mov_b32_e32 v33, v10
	v_mov_b32_e32 v98, v10
	v_mov_b32_e32 v99, v10
	v_mov_b32_e32 v100, v10
	v_mov_b32_e32 v101, v10
	v_mov_b32_e32 v102, v10
	v_mov_b32_e32 v103, v10
	v_mov_b32_e32 v104, v10
	v_mov_b32_e32 v105, v10
	v_mov_b32_e32 v106, v10
	v_mov_b32_e32 v107, v10
	v_mov_b32_e32 v108, v10
	v_mov_b32_e32 v109, v10
	v_mov_b32_e32 v110, v10
	v_mov_b32_e32 v111, v10
	v_mov_b32_e32 v112, v10
	v_mov_b32_e32 v113, v10
	v_mov_b32_e32 v114, v10
	v_mov_b32_e32 v115, v10
	v_mov_b32_e32 v116, v10
	v_mov_b32_e32 v117, v10
	v_mov_b32_e32 v118, v10
	v_mov_b32_e32 v119, v10
	v_mov_b32_e32 v120, v10
	v_mov_b32_e32 v121, v10
	v_mov_b32_e32 v122, v10
	v_mov_b32_e32 v123, v10
	v_mov_b32_e32 v124, v10
	v_mov_b32_e32 v125, v10
	v_mov_b32_e32 v126, v10
	v_mov_b32_e32 v127, v10
	v_mov_b32_e32 v128, v10
	v_mov_b32_e32 v129, v10
	s_nop 0
